# GEMM phase prologues de-serialised: the second k-tile's 6 LDS-DMA loads are issued before (not after) the wait+barrier for the first tile (vmcnt(2)->vmcnt(8), barrier moved)
# speedup vs baseline: 1.0133x; 1.0133x over previous
; #define PG8_STAGE(bufoff, gbase, voff) do { _Pragma("unroll") for (int _i = 0; _i < 2; ++_i) \
;         __builtin_amdgcn_global_load_lds((const unsigned*)((const char*)(gbase) + (voff)[_i]), (LAS unsigned*)(lds + (bufoff) + ldsw + _i * 8192), 16, 0, 0); } while (0)
; #define PG8_WAIT_V(n) asm volatile("s_waitcnt vmcnt(" #n ")" ::: "memory")
; #define PG8_BAR __builtin_amdgcn_s_barrier()
; template <class Epi>
; __device__ __forceinline__ void gemm_phase(LAS unsigned char* lds, const int tid, const Gemm g, const StaticOrder& S, const Epi& E) {
;     ...
;     for (int i = 0; i < 2; ++i) { int R, C; stage_rc(tid * 16 + i * 8192, R, C); const int Rb = (R & ~31) + perm32(R & 31);
;         voffA[i] = (unsigned)(R * g.lda + C) * 2u; voffB[i] = (unsigned)(Rb * g.ldb + C) * 2u; }
;     const size_t kstep = (size_t)(BK * 2);
;     const size_t hstepA = (size_t)HALF * g.lda * 2, hstepB = (size_t)HALF * g.ldb * 2;
;     const size_t tstepA = 2 * hstepA, tstepB = 2 * hstepB;
;     const unsigned ldsw = (unsigned)wid * 1024u;
;     const int aoff = lds_byte(wr * 64 + fr, fq * 8), boff = lds_byte(wc * 32 + fr, fq * 8);
;     ...
;     PG8_STAGE(PG8_SB(0, 0), cB, voffB); PG8_STAGE(PG8_SB(0, 1), cB + hstepB, voffB); PG8_STAGE(PG8_SA(0, 0), cA, voffA); PG8_STAGE(PG8_SA(0, 1), cA + hstepA, voffA);
;     if (wr == 1) PG8_BAR;
;     PG8_WAIT_V(2); PG8_BAR;
;     PG8_STAGE(PG8_SB(1, 0), cB + kstep, voffB); PG8_STAGE(PG8_SA(1, 0), cA + kstep, voffA); PG8_STAGE(PG8_SB(1, 1), cB + hstepB + kstep, voffB);
;     PG8_WAIT_V(6); PG8_BAR;
.LBB0_256:
	s_add_u32 s10, s6, 0xe100000
	s_addc_u32 s11, s7, 0
	s_ashr_i32 s13, s4, 31
	s_lshr_b32 s13, s13, 26
	s_add_i32 s13, s4, s13
	s_lshl_b32 s12, s12, 5
	s_ashr_i32 s46, s13, 6
	s_and_b32 s17, s12, 0x60
	s_mov_b64 s[12:13], 0x80
	s_add_i32 m0, s41, 0x18000
	v_lshl_add_u64 v[8:9], v[8:9], 0, s[12:13]
	s_lshl_b32 s16, s5, 13
	s_lshl_b32 s18, s17, 7
	global_load_lds_dwordx4 v[8:9], off
	v_lshl_add_u64 v[6:7], v[6:7], 0, s[12:13]
	s_add_i32 m0, s41, 0x1a000
	s_add_i32 s47, s41, 0x8000
	s_add_i32 s48, s41, 0xa000
	global_load_lds_dwordx4 v[6:7], off
	v_lshl_add_u64 v[2:3], v[2:3], 0, s[12:13]
	s_mov_b32 m0, s47
	s_add_u32 s14, s26, 0x40080
	global_load_lds_dwordx4 v[2:3], off
	v_lshl_add_u64 v[2:3], v[4:5], 0, s[12:13]
	s_mov_b32 m0, s48
	s_addc_u32 s15, s27, 0
	global_load_lds_dwordx4 v[2:3], off
	s_add_i32 m0, s41, 0x1c000
	v_lshl_add_u64 v[2:3], s[14:15], 0, v[132:133]
	global_load_lds_dwordx4 v[2:3], off
	v_lshl_add_u64 v[2:3], s[14:15], 0, v[128:129]
	s_add_i32 m0, s41, 0x1e000
	v_lshl_add_u64 v[0:1], v[0:1], 4, s[6:7]
	global_load_lds_dwordx4 v[2:3], off
	s_mov_b64 s[6:7], 0x1f100000
	v_lshl_add_u64 v[136:137], v[0:1], 0, s[6:7]
	v_lshlrev_b32_e32 v0, 14, v10
	v_and_b32_e32 v0, 0xffff8000, v0
	v_lshl_add_u32 v0, v12, 11, v0
	v_and_b32_e32 v1, 1, v10
	v_lshl_or_b32 v0, v1, 6, v0
	v_and_b32_e32 v3, 15, v11
	v_lshl_add_u32 v138, v13, 1, v0
	v_lshlrev_b32_e32 v0, 14, v15
	v_bfe_u32 v2, v11, 4, 2
	v_lshl_or_b32 v150, s5, 6, v3
	v_and_b32_e32 v0, 0xffff8000, v0
	s_sext_i32_i16 s54, s2
	v_lshlrev_b32_e32 v4, 6, v150
	v_lshlrev_b32_e32 v5, 4, v2
	s_movk_i32 s2, 0x3c0
	v_lshlrev_b32_e32 v7, 2, v11
	s_cmp_gt_i32 s4, 63
	v_lshl_add_u32 v0, v14, 11, v0
	v_and_b32_e32 v1, 1, v15
	v_and_or_b32 v6, v4, s2, v5
	v_and_b32_e32 v7, 32, v7
	v_lshl_or_b32 v3, v3, 6, v5
	s_waitcnt vmcnt(8)
	s_barrier
	s_waitcnt vmcnt(6)
	s_cselect_b64 s[4:5], -1, 0
	s_add_i32 s2, 0, 0x20800
	s_add_i32 s49, s46, -2
	v_lshl_or_b32 v0, v1, 6, v0
	v_bitop3_b32 v6, v6, s16, v7 bitop3:0xde
	v_bitop3_b32 v151, s18, v3, v7 bitop3:0xf6
	v_add_u32_e32 v3, s2, v4
	s_cmpk_lt_u32 s3, 0x100
	v_lshl_add_u32 v140, v16, 1, v0
	v_cndmask_b32_e64 v0, 0, 1, s[4:5]
	s_cselect_b64 s[6:7], -1, 0
	s_ashr_i32 s50, s92, 31
	v_lshl_or_b32 v152, v2, 3, s17
	v_mov_b32_e32 v139, v133
	v_mov_b32_e32 v141, v133
	v_mov_b64_e32 v[142:143], 0xb00
	v_mov_b64_e32 v[144:145], 0xaff
	s_mov_b64 s[14:15], 0x2000
	s_add_i32 s51, 0, 0x10000
	s_add_i32 s52, 0, 0x14000
	v_add_u32_e32 v153, 0, v6
	v_add_u32_e32 v154, v3, v5
	v_mov_b32_e32 v155, 0x358637bd
	s_movk_i32 s53, 0x1600
	v_cmp_ne_u32_e64 s[2:3], 1, v0
	s_barrier
	s_waitcnt vmcnt(0)
	s_branch .LBB0_259

; #define PG8_STAGE(bufoff, gbase, voff) do { _Pragma("unroll") for (int _i = 0; _i < 2; ++_i) \
;         __builtin_amdgcn_global_load_lds((const unsigned*)((const char*)(gbase) + (voff)[_i]), (LAS unsigned*)(lds + (bufoff) + ldsw + _i * 8192), 16, 0, 0); } while (0)
; #define PG8_WAIT_V(n) asm volatile("s_waitcnt vmcnt(" #n ")" ::: "memory")
; #define PG8_BAR __builtin_amdgcn_s_barrier()
; template <class Epi>
; __device__ __forceinline__ void gemm_phase(LAS unsigned char* lds, const int tid, const Gemm g, const StaticOrder& S, const Epi& E) {
;     ...
;     for (int i = 0; i < 2; ++i) { int R, C; stage_rc(tid * 16 + i * 8192, R, C); const int Rb = (R & ~31) + perm32(R & 31);
;         voffA[i] = (unsigned)(R * g.lda + C) * 2u; voffB[i] = (unsigned)(Rb * g.ldb + C) * 2u; }
;     const size_t kstep = (size_t)(BK * 2);
;     const size_t hstepA = (size_t)HALF * g.lda * 2, hstepB = (size_t)HALF * g.ldb * 2;
;     const size_t tstepA = 2 * hstepA, tstepB = 2 * hstepB;
;     const unsigned ldsw = (unsigned)wid * 1024u;
;     const int aoff = lds_byte(wr * 64 + fr, fq * 8), boff = lds_byte(wc * 32 + fr, fq * 8);
;     ...
;     PG8_STAGE(PG8_SB(0, 0), cB, voffB); PG8_STAGE(PG8_SB(0, 1), cB + hstepB, voffB); PG8_STAGE(PG8_SA(0, 0), cA, voffA); PG8_STAGE(PG8_SA(0, 1), cA + hstepA, voffA);
;     if (wr == 1) PG8_BAR;
;     PG8_WAIT_V(2); PG8_BAR;
;     PG8_STAGE(PG8_SB(1, 0), cB + kstep, voffB); PG8_STAGE(PG8_SA(1, 0), cA + kstep, voffA); PG8_STAGE(PG8_SB(1, 1), cB + hstepB + kstep, voffB);
;     PG8_WAIT_V(6); PG8_BAR;
.LBB0_337:
	s_add_u32 s14, s2, 0x6100000
	s_addc_u32 s15, s3, 0
	s_add_u32 s16, s2, 0x1f300000
	s_addc_u32 s17, s3, 0
	s_ashr_i32 s2, s20, 31
	s_lshr_b32 s2, s2, 26
	s_mov_b64 s[18:19], 0x80
	s_and_b32 s45, s5, 3
	s_add_i32 s2, s20, s2
	s_add_i32 m0, s41, 0x18000
	v_lshl_add_u64 v[6:7], v[6:7], 0, s[18:19]
	s_ashr_i32 s46, s2, 6
	s_lshl_b32 s5, s6, 13
	s_lshl_b32 s7, s45, 12
	global_load_lds_dwordx4 v[6:7], off
	v_lshl_add_u64 v[4:5], v[4:5], 0, s[18:19]
	s_add_i32 m0, s41, 0x1a000
	s_add_i32 s47, s41, 0x8000
	s_add_i32 s48, s41, 0xa000
	global_load_lds_dwordx4 v[4:5], off
	v_lshl_add_u64 v[0:1], v[0:1], 0, s[18:19]
	s_mov_b32 m0, s47
	s_add_u32 s2, s28, 0xb0080
	global_load_lds_dwordx4 v[0:1], off
	v_lshl_add_u64 v[0:1], v[2:3], 0, s[18:19]
	s_mov_b32 m0, s48
	s_addc_u32 s3, s29, 0
	global_load_lds_dwordx4 v[0:1], off
	s_add_i32 m0, s41, 0x1c000
	v_lshl_add_u64 v[0:1], s[2:3], 0, v[130:131]
	global_load_lds_dwordx4 v[0:1], off
	v_lshl_add_u64 v[0:1], s[2:3], 0, v[134:135]
	s_add_i32 m0, s41, 0x1e000
	s_cmp_gt_i32 s20, 63
	global_load_lds_dwordx4 v[0:1], off
	v_bfe_u32 v0, v8, 4, 2
	v_and_b32_e32 v1, 15, v8
	v_lshlrev_b32_e32 v3, 4, v0
	v_lshl_or_b32 v204, s6, 6, v1
	v_lshl_or_b32 v1, v1, 6, v3
	v_lshlrev_b32_e32 v3, 2, v8
	v_and_b32_e32 v3, 32, v3
	v_lshlrev_b32_e32 v2, 3, v0
	v_bitop3_b32 v4, v1, s5, v3 bitop3:0xde
	v_bitop3_b32 v205, s7, v1, v3 bitop3:0xf6
	v_cmp_eq_u32_e64 s[2:3], 0, v0
	v_lshrrev_b32_e32 v1, 1, v13
	v_mul_lo_u32 v0, v15, s4
	s_mov_b32 s5, 0xb000
	v_mad_u64_u32 v[0:1], s[24:25], v1, s5, v[0:1]
	v_or_b32_e32 v0, v0, v14
	s_mov_b64 s[6:7], 0xb0080
	v_add_lshl_u32 v0, v0, v16, 1
	v_mov_b32_e32 v1, v131
	v_lshl_add_u64 v[136:137], v[0:1], 0, s[6:7]
	v_lshrrev_b32_e32 v1, 1, v9
	v_mul_lo_u32 v0, v10, s4
	s_cselect_b64 s[20:21], -1, 0
	s_add_i32 s49, s46, -2
	v_mad_u64_u32 v[0:1], s[4:5], v1, s5, v[0:1]
	s_waitcnt vmcnt(8)
	s_barrier
	s_waitcnt vmcnt(6)
	s_cmpk_lt_u32 s22, 0x100
	v_or_b32_e32 v0, v0, v11
	s_cselect_b64 s[22:23], -1, 0
	v_add_lshl_u32 v0, v0, v12, 1
	v_mov_b32_e32 v1, v131
	s_add_i32 s52, 0, 0x10000
	s_add_i32 s53, 0, 0x14000
	v_lshl_or_b32 v206, s45, 5, v2
	s_ashr_i32 s50, s92, 31
	s_ashr_i32 s51, s33, 31
	v_lshl_add_u64 v[138:139], v[0:1], 0, s[6:7]
	v_mov_b64_e32 v[140:141], 0x200
	v_mov_b64_e32 v[142:143], 0x1ff
	v_add_u32_e32 v207, s52, v205
	v_add_u32_e32 v208, s53, v205
	v_add_u32_e32 v209, 0, v4
	s_mov_b32 s54, 0
	s_barrier
	s_branch .LBB0_340

; #define PG8_STAGE(bufoff, gbase, voff) do { _Pragma("unroll") for (int _i = 0; _i < 2; ++_i) \
;         __builtin_amdgcn_global_load_lds((const unsigned*)((const char*)(gbase) + (voff)[_i]), (LAS unsigned*)(lds + (bufoff) + ldsw + _i * 8192), 16, 0, 0); } while (0)
; #define PG8_WAIT_V(n) asm volatile("s_waitcnt vmcnt(" #n ")" ::: "memory")
; #define PG8_BAR __builtin_amdgcn_s_barrier()
; template <class Epi>
; __device__ __forceinline__ void gemm_phase(LAS unsigned char* lds, const int tid, const Gemm g, const StaticOrder& S, const Epi& E) {
;     ...
;     for (int i = 0; i < 2; ++i) { int R, C; stage_rc(tid * 16 + i * 8192, R, C); const int Rb = (R & ~31) + perm32(R & 31);
;         voffA[i] = (unsigned)(R * g.lda + C) * 2u; voffB[i] = (unsigned)(Rb * g.ldb + C) * 2u; }
;     const size_t kstep = (size_t)(BK * 2);
;     const size_t hstepA = (size_t)HALF * g.lda * 2, hstepB = (size_t)HALF * g.ldb * 2;
;     const size_t tstepA = 2 * hstepA, tstepB = 2 * hstepB;
;     const unsigned ldsw = (unsigned)wid * 1024u;
;     const int aoff = lds_byte(wr * 64 + fr, fq * 8), boff = lds_byte(wc * 32 + fr, fq * 8);
;     ...
;     PG8_STAGE(PG8_SB(0, 0), cB, voffB); PG8_STAGE(PG8_SB(0, 1), cB + hstepB, voffB); PG8_STAGE(PG8_SA(0, 0), cA, voffA); PG8_STAGE(PG8_SA(0, 1), cA + hstepA, voffA);
;     if (wr == 1) PG8_BAR;
;     PG8_WAIT_V(2); PG8_BAR;
;     PG8_STAGE(PG8_SB(1, 0), cB + kstep, voffB); PG8_STAGE(PG8_SA(1, 0), cA + kstep, voffA); PG8_STAGE(PG8_SB(1, 1), cB + hstepB + kstep, voffB);
;     PG8_WAIT_V(6); PG8_BAR;
.LBB0_435:
	s_add_u32 s14, s6, 0x10100000
	s_addc_u32 s15, s7, 0
	s_and_b32 s54, s16, 3
	s_ashr_i32 s16, s4, 31
	s_lshr_b32 s16, s16, 26
	s_add_i32 s16, s4, s16
	s_ashr_i32 s55, s16, 6
	s_mov_b64 s[16:17], 0x80
	s_add_i32 m0, s50, 0x18000
	v_lshl_add_u64 v[8:9], v[8:9], 0, s[16:17]
	s_lshl_b32 s19, s18, 13
	s_lshl_b32 s56, s54, 5
	s_lshl_b32 s22, s54, 12
	global_load_lds_dwordx4 v[8:9], off
	v_lshl_add_u64 v[6:7], v[6:7], 0, s[16:17]
	s_add_i32 m0, s50, 0x1a000
	s_add_i32 s57, s50, 0x8000
	s_add_i32 s58, s50, 0xa000
	global_load_lds_dwordx4 v[6:7], off
	v_lshl_add_u64 v[2:3], v[2:3], 0, s[16:17]
	s_mov_b32 m0, s57
	s_add_u32 s20, s36, 0x40080
	global_load_lds_dwordx4 v[2:3], off
	v_lshl_add_u64 v[2:3], v[4:5], 0, s[16:17]
	s_mov_b32 m0, s58
	s_addc_u32 s21, s37, 0
	global_load_lds_dwordx4 v[2:3], off
	s_add_i32 m0, s50, 0x1c000
	v_lshl_add_u64 v[2:3], s[20:21], 0, v[132:133]
	global_load_lds_dwordx4 v[2:3], off
	v_lshl_add_u64 v[2:3], s[20:21], 0, v[128:129]
	s_add_i32 m0, s50, 0x1e000
	s_sext_i32_i8 s33, s2
	global_load_lds_dwordx4 v[2:3], off
	v_and_b32_e32 v3, 15, v11
	v_bfe_u32 v2, v11, 4, 2
	v_lshl_or_b32 v139, s18, 6, v3
	v_lshlrev_b32_e32 v4, 6, v139
	v_lshlrev_b32_e32 v170, 4, v2
	s_movk_i32 s2, 0x3c0
	v_lshlrev_b32_e32 v5, 2, v11
	v_lshlrev_b32_e32 v138, 3, v2
	v_and_or_b32 v2, v4, s2, v170
	v_and_b32_e32 v5, 32, v5
	s_cmp_gt_i32 s4, 63
	v_bitop3_b32 v2, v2, s19, v5 bitop3:0xde
	s_cselect_b64 s[18:19], -1, 0
	s_add_i32 s2, 0, 0x20800
	s_add_i32 s59, s55, -2
	v_add_u32_e32 v172, s2, v4
	s_cmpk_lt_u32 s3, 0x100
	v_lshl_add_u64 v[0:1], v[0:1], 4, s[6:7]
	s_mov_b64 s[2:3], 0x1f300000
	v_lshl_add_u64 v[140:141], v[0:1], 0, s[2:3]
	v_lshlrev_b32_e32 v0, 14, v10
	v_and_b32_e32 v0, 0xffff8000, v0
	v_lshl_add_u32 v0, v12, 11, v0
	v_and_b32_e32 v1, 1, v10
	v_lshl_or_b32 v0, v1, 6, v0
	v_lshl_add_u32 v142, v13, 1, v0
	v_lshlrev_b32_e32 v0, 14, v15
	v_and_b32_e32 v0, 0xffff8000, v0
	s_waitcnt vmcnt(8)
	s_barrier
	s_waitcnt vmcnt(6)
	v_lshl_add_u32 v0, v14, 11, v0
	v_and_b32_e32 v1, 1, v15
	v_lshl_or_b32 v3, v3, 6, v170
	v_lshl_or_b32 v0, v1, 6, v0
	v_bitop3_b32 v171, s22, v3, v5 bitop3:0xf6
	s_cselect_b64 s[20:21], -1, 0
	s_ashr_i32 s60, s92, 31
	v_mov_b32_e32 v143, v137
	v_lshl_add_u32 v144, v16, 1, v0
	v_mov_b32_e32 v145, v137
	v_mov_b64_e32 v[146:147], 0x600
	v_mov_b64_e32 v[148:149], 0x5ff
	s_mov_b64 s[22:23], 0x2000
	s_add_i32 s61, 0, 0x10000
	s_add_i32 s62, 0, 0x14000
	v_add_u32_e32 v173, 0, v2
	s_mov_b32 s63, 0x12100000
	v_mov_b32_e32 v174, 0x358637bd
	s_mov_b32 s64, 0xe100000
	v_mov_b32_e32 v175, 0x3e38aa3b
	s_mov_b32 s65, 0
	s_barrier
	s_branch .LBB0_438

; #define PG8_STAGE(bufoff, gbase, voff) do { _Pragma("unroll") for (int _i = 0; _i < 2; ++_i) \
;         __builtin_amdgcn_global_load_lds((const unsigned*)((const char*)(gbase) + (voff)[_i]), (LAS unsigned*)(lds + (bufoff) + ldsw + _i * 8192), 16, 0, 0); } while (0)
; #define PG8_WAIT_V(n) asm volatile("s_waitcnt vmcnt(" #n ")" ::: "memory")
; #define PG8_BAR __builtin_amdgcn_s_barrier()
; template <class Epi>
; __device__ __forceinline__ void gemm_phase(LAS unsigned char* lds, const int tid, const Gemm g, const StaticOrder& S, const Epi& E) {
;     ...
;     for (int i = 0; i < 2; ++i) { int R, C; stage_rc(tid * 16 + i * 8192, R, C); const int Rb = (R & ~31) + perm32(R & 31);
;         voffA[i] = (unsigned)(R * g.lda + C) * 2u; voffB[i] = (unsigned)(Rb * g.ldb + C) * 2u; }
;     const size_t kstep = (size_t)(BK * 2);
;     const size_t hstepA = (size_t)HALF * g.lda * 2, hstepB = (size_t)HALF * g.ldb * 2;
;     const size_t tstepA = 2 * hstepA, tstepB = 2 * hstepB;
;     const unsigned ldsw = (unsigned)wid * 1024u;
;     const int aoff = lds_byte(wr * 64 + fr, fq * 8), boff = lds_byte(wc * 32 + fr, fq * 8);
;     ...
;     PG8_STAGE(PG8_SB(0, 0), cB, voffB); PG8_STAGE(PG8_SB(0, 1), cB + hstepB, voffB); PG8_STAGE(PG8_SA(0, 0), cA, voffA); PG8_STAGE(PG8_SA(0, 1), cA + hstepA, voffA);
;     if (wr == 1) PG8_BAR;
;     PG8_WAIT_V(2); PG8_BAR;
;     PG8_STAGE(PG8_SB(1, 0), cB + kstep, voffB); PG8_STAGE(PG8_SA(1, 0), cA + kstep, voffA); PG8_STAGE(PG8_SB(1, 1), cB + hstepB + kstep, voffB);
;     PG8_WAIT_V(6); PG8_BAR;
.LBB0_717:
	s_add_u32 s12, s6, 0x6100000
	s_addc_u32 s13, s7, 0
	s_add_u32 s6, s6, 0x1f100000
	s_addc_u32 s7, s7, 0
	s_and_b32 s47, s2, 3
	s_ashr_i32 s2, s16, 31
	s_lshr_b32 s2, s2, 26
	s_mov_b64 s[14:15], 0x80
	s_add_i32 s2, s16, s2
	s_add_i32 m0, s43, 0x18000
	v_lshl_add_u64 v[6:7], v[6:7], 0, s[14:15]
	s_ashr_i32 s48, s2, 6
	s_lshl_b32 s2, s3, 13
	s_lshl_b32 s17, s47, 12
	global_load_lds_dwordx4 v[6:7], off
	v_lshl_add_u64 v[4:5], v[4:5], 0, s[14:15]
	s_add_i32 m0, s43, 0x1a000
	s_add_i32 s49, s43, 0x8000
	s_add_i32 s50, s43, 0xa000
	global_load_lds_dwordx4 v[4:5], off
	v_lshl_add_u64 v[0:1], v[0:1], 0, s[14:15]
	s_mov_b32 m0, s49
	s_add_u32 s4, s30, 0x40080
	global_load_lds_dwordx4 v[0:1], off
	v_lshl_add_u64 v[0:1], v[2:3], 0, s[14:15]
	s_mov_b32 m0, s50
	s_addc_u32 s5, s31, 0
	global_load_lds_dwordx4 v[0:1], off
	s_add_i32 m0, s43, 0x1c000
	v_lshl_add_u64 v[0:1], s[4:5], 0, v[154:155]
	global_load_lds_dwordx4 v[0:1], off
	v_lshl_add_u64 v[0:1], s[4:5], 0, v[158:159]
	s_add_i32 m0, s43, 0x1e000
	s_cmp_gt_i32 s16, 63
	global_load_lds_dwordx4 v[0:1], off
	v_bfe_u32 v0, v8, 4, 2
	v_and_b32_e32 v1, 15, v8
	v_lshlrev_b32_e32 v3, 4, v0
	v_lshl_or_b32 v186, s3, 6, v1
	v_lshl_or_b32 v1, v1, 6, v3
	v_lshlrev_b32_e32 v3, 2, v8
	v_and_b32_e32 v3, 32, v3
	v_lshlrev_b32_e32 v2, 3, v0
	v_bitop3_b32 v4, v1, s2, v3 bitop3:0xde
	v_cmp_eq_u32_e64 s[2:3], 0, v0
	v_lshlrev_b32_e32 v0, 14, v12
	v_and_b32_e32 v0, 0xffff8000, v0
	v_bitop3_b32 v187, s17, v1, v3 bitop3:0xf6
	v_lshl_add_u32 v0, v13, 11, v0
	v_and_b32_e32 v1, 1, v12
	v_lshl_or_b32 v0, v1, 6, v0
	v_lshl_add_u32 v160, v14, 1, v0
	v_lshlrev_b32_e32 v0, 14, v9
	s_cselect_b64 s[16:17], -1, 0
	s_add_i32 s51, s48, -2
	v_and_b32_e32 v0, 0xffff8000, v0
	s_waitcnt vmcnt(8)
	s_barrier
	s_waitcnt vmcnt(6)
	s_cmpk_lt_u32 s18, 0x100
	v_lshl_add_u32 v0, v10, 11, v0
	v_and_b32_e32 v1, 1, v9
	s_cselect_b64 s[18:19], -1, 0
	v_lshl_or_b32 v0, v1, 6, v0
	s_add_i32 s54, 0, 0x10000
	s_add_i32 s55, 0, 0x14000
	v_lshl_or_b32 v188, s47, 5, v2
	s_ashr_i32 s52, s92, 31
	s_ashr_i32 s53, s33, 31
	v_mov_b32_e32 v161, v155
	v_lshl_add_u32 v162, v11, 1, v0
	v_mov_b32_e32 v163, v155
	v_mov_b64_e32 v[164:165], 0x200
	v_mov_b64_e32 v[166:167], 0x1ff
	v_add_u32_e32 v189, s54, v187
	v_add_u32_e32 v190, s55, v187
	v_add_u32_e32 v191, 0, v4
	s_mov_b32 s56, 0
	s_barrier
	s_branch .LBB0_720

; #define PG8_STAGE(bufoff, gbase, voff) do { _Pragma("unroll") for (int _i = 0; _i < 2; ++_i) \
;         __builtin_amdgcn_global_load_lds((const unsigned*)((const char*)(gbase) + (voff)[_i]), (LAS unsigned*)(lds + (bufoff) + ldsw + _i * 8192), 16, 0, 0); } while (0)
; #define PG8_WAIT_V(n) asm volatile("s_waitcnt vmcnt(" #n ")" ::: "memory")
; #define PG8_BAR __builtin_amdgcn_s_barrier()
; template <class Epi>
; __device__ __forceinline__ void gemm_phase(LAS unsigned char* lds, const int tid, const Gemm g, const StaticOrder& S, const Epi& E) {
;     ...
;     for (int i = 0; i < 2; ++i) { int R, C; stage_rc(tid * 16 + i * 8192, R, C); const int Rb = (R & ~31) + perm32(R & 31);
;         voffA[i] = (unsigned)(R * g.lda + C) * 2u; voffB[i] = (unsigned)(Rb * g.ldb + C) * 2u; }
;     const size_t kstep = (size_t)(BK * 2);
;     const size_t hstepA = (size_t)HALF * g.lda * 2, hstepB = (size_t)HALF * g.ldb * 2;
;     const size_t tstepA = 2 * hstepA, tstepB = 2 * hstepB;
;     const unsigned ldsw = (unsigned)wid * 1024u;
;     const int aoff = lds_byte(wr * 64 + fr, fq * 8), boff = lds_byte(wc * 32 + fr, fq * 8);
;     ...
;     PG8_STAGE(PG8_SB(0, 0), cB, voffB); PG8_STAGE(PG8_SB(0, 1), cB + hstepB, voffB); PG8_STAGE(PG8_SA(0, 0), cA, voffA); PG8_STAGE(PG8_SA(0, 1), cA + hstepA, voffA);
;     if (wr == 1) PG8_BAR;
;     PG8_WAIT_V(2); PG8_BAR;
;     PG8_STAGE(PG8_SB(1, 0), cB + kstep, voffB); PG8_STAGE(PG8_SA(1, 0), cA + kstep, voffA); PG8_STAGE(PG8_SB(1, 1), cB + hstepB + kstep, voffB);
;     PG8_WAIT_V(6); PG8_BAR;
.LBB0_810:
	s_add_u32 s10, s6, 0xe100000
	s_addc_u32 s11, s7, 0
	s_ashr_i32 s13, s4, 31
	s_lshr_b32 s13, s13, 26
	s_add_i32 s13, s4, s13
	s_lshl_b32 s12, s12, 5
	s_ashr_i32 s46, s13, 6
	s_and_b32 s17, s12, 0x60
	s_mov_b64 s[12:13], 0x80
	s_add_i32 m0, s41, 0x18000
	v_lshl_add_u64 v[8:9], v[8:9], 0, s[12:13]
	s_lshl_b32 s16, s5, 13
	s_lshl_b32 s18, s17, 7
	global_load_lds_dwordx4 v[8:9], off
	v_lshl_add_u64 v[6:7], v[6:7], 0, s[12:13]
	s_add_i32 m0, s41, 0x1a000
	s_add_i32 s47, s41, 0x8000
	s_add_i32 s48, s41, 0xa000
	global_load_lds_dwordx4 v[6:7], off
	v_lshl_add_u64 v[2:3], v[2:3], 0, s[12:13]
	s_mov_b32 m0, s47
	s_add_u32 s14, s26, 0x40080
	global_load_lds_dwordx4 v[2:3], off
	v_lshl_add_u64 v[2:3], v[4:5], 0, s[12:13]
	s_mov_b32 m0, s48
	s_addc_u32 s15, s27, 0
	global_load_lds_dwordx4 v[2:3], off
	s_add_i32 m0, s41, 0x1c000
	v_lshl_add_u64 v[2:3], s[14:15], 0, v[132:133]
	global_load_lds_dwordx4 v[2:3], off
	v_lshl_add_u64 v[2:3], s[14:15], 0, v[128:129]
	s_add_i32 m0, s41, 0x1e000
	v_lshl_add_u64 v[0:1], v[0:1], 4, s[6:7]
	global_load_lds_dwordx4 v[2:3], off
	s_mov_b64 s[6:7], 0x1f100000
	v_lshl_add_u64 v[136:137], v[0:1], 0, s[6:7]
	v_lshlrev_b32_e32 v0, 14, v10
	v_and_b32_e32 v0, 0xffff8000, v0
	v_lshl_add_u32 v0, v12, 11, v0
	v_and_b32_e32 v1, 1, v10
	v_lshl_or_b32 v0, v1, 6, v0
	v_and_b32_e32 v3, 15, v11
	v_lshl_add_u32 v138, v13, 1, v0
	v_lshlrev_b32_e32 v0, 14, v15
	v_bfe_u32 v2, v11, 4, 2
	v_lshl_or_b32 v150, s5, 6, v3
	v_and_b32_e32 v0, 0xffff8000, v0
	s_sext_i32_i16 s54, s2
	v_lshlrev_b32_e32 v4, 6, v150
	v_lshlrev_b32_e32 v5, 4, v2
	s_movk_i32 s2, 0x3c0
	v_lshlrev_b32_e32 v7, 2, v11
	s_cmp_gt_i32 s4, 63
	v_lshl_add_u32 v0, v14, 11, v0
	v_and_b32_e32 v1, 1, v15
	v_and_or_b32 v6, v4, s2, v5
	v_and_b32_e32 v7, 32, v7
	v_lshl_or_b32 v3, v3, 6, v5
	s_waitcnt vmcnt(8)
	s_barrier
	s_waitcnt vmcnt(6)
	s_cselect_b64 s[4:5], -1, 0
	s_add_i32 s2, 0, 0x20800
	s_add_i32 s49, s46, -2
	v_lshl_or_b32 v0, v1, 6, v0
	v_bitop3_b32 v6, v6, s16, v7 bitop3:0xde
	v_bitop3_b32 v151, s18, v3, v7 bitop3:0xf6
	v_add_u32_e32 v3, s2, v4
	s_cmpk_lt_u32 s3, 0x100
	v_lshl_add_u32 v140, v16, 1, v0
	v_cndmask_b32_e64 v0, 0, 1, s[4:5]
	s_cselect_b64 s[6:7], -1, 0
	s_ashr_i32 s50, s92, 31
	v_lshl_or_b32 v152, v2, 3, s17
	v_mov_b32_e32 v139, v133
	v_mov_b32_e32 v141, v133
	v_mov_b64_e32 v[142:143], 0xb00
	v_mov_b64_e32 v[144:145], 0xaff
	s_mov_b64 s[14:15], 0x2000
	s_add_i32 s51, 0, 0x10000
	s_add_i32 s52, 0, 0x14000
	v_add_u32_e32 v153, 0, v6
	v_add_u32_e32 v154, v3, v5
	v_mov_b32_e32 v155, 0x358637bd
	s_movk_i32 s53, 0x1600
	v_cmp_ne_u32_e64 s[2:3], 1, v0
	s_barrier
	s_branch .LBB0_813

; #define PG8_STAGE(bufoff, gbase, voff) do { _Pragma("unroll") for (int _i = 0; _i < 2; ++_i) \
;         __builtin_amdgcn_global_load_lds((const unsigned*)((const char*)(gbase) + (voff)[_i]), (LAS unsigned*)(lds + (bufoff) + ldsw + _i * 8192), 16, 0, 0); } while (0)
; #define PG8_WAIT_V(n) asm volatile("s_waitcnt vmcnt(" #n ")" ::: "memory")
; #define PG8_BAR __builtin_amdgcn_s_barrier()
; template <class Epi>
; __device__ __forceinline__ void gemm_phase(LAS unsigned char* lds, const int tid, const Gemm g, const StaticOrder& S, const Epi& E) {
;     ...
;     for (int i = 0; i < 2; ++i) { int R, C; stage_rc(tid * 16 + i * 8192, R, C); const int Rb = (R & ~31) + perm32(R & 31);
;         voffA[i] = (unsigned)(R * g.lda + C) * 2u; voffB[i] = (unsigned)(Rb * g.ldb + C) * 2u; }
;     const size_t kstep = (size_t)(BK * 2);
;     const size_t hstepA = (size_t)HALF * g.lda * 2, hstepB = (size_t)HALF * g.ldb * 2;
;     const size_t tstepA = 2 * hstepA, tstepB = 2 * hstepB;
;     const unsigned ldsw = (unsigned)wid * 1024u;
;     const int aoff = lds_byte(wr * 64 + fr, fq * 8), boff = lds_byte(wc * 32 + fr, fq * 8);
;     ...
;     PG8_STAGE(PG8_SB(0, 0), cB, voffB); PG8_STAGE(PG8_SB(0, 1), cB + hstepB, voffB); PG8_STAGE(PG8_SA(0, 0), cA, voffA); PG8_STAGE(PG8_SA(0, 1), cA + hstepA, voffA);
;     if (wr == 1) PG8_BAR;
;     PG8_WAIT_V(2); PG8_BAR;
;     PG8_STAGE(PG8_SB(1, 0), cB + kstep, voffB); PG8_STAGE(PG8_SA(1, 0), cA + kstep, voffA); PG8_STAGE(PG8_SB(1, 1), cB + hstepB + kstep, voffB);
;     PG8_WAIT_V(6); PG8_BAR;
.LBB0_891:
	s_add_u32 s12, s6, 0x6100000
	s_addc_u32 s13, s7, 0
	s_add_u32 s14, s6, 0x1f300000
	s_addc_u32 s15, s7, 0
	s_and_b32 s43, s2, 3
	s_ashr_i32 s2, s18, 31
	s_lshr_b32 s2, s2, 26
	s_mov_b64 s[16:17], 0x80
	s_add_i32 s2, s18, s2
	s_add_i32 m0, s39, 0x18000
	v_lshl_add_u64 v[6:7], v[6:7], 0, s[16:17]
	s_ashr_i32 s44, s2, 6
	s_lshl_b32 s2, s3, 13
	s_lshl_b32 s5, s43, 12
	global_load_lds_dwordx4 v[6:7], off
	v_lshl_add_u64 v[4:5], v[4:5], 0, s[16:17]
	s_add_i32 m0, s39, 0x1a000
	s_add_i32 s45, s39, 0x8000
	s_add_i32 s46, s39, 0xa000
	global_load_lds_dwordx4 v[4:5], off
	v_lshl_add_u64 v[0:1], v[0:1], 0, s[16:17]
	s_mov_b32 m0, s45
	s_add_u32 s6, s26, 0xb0080
	global_load_lds_dwordx4 v[0:1], off
	v_lshl_add_u64 v[0:1], v[2:3], 0, s[16:17]
	s_mov_b32 m0, s46
	s_addc_u32 s7, s27, 0
	global_load_lds_dwordx4 v[0:1], off
	s_add_i32 m0, s39, 0x1c000
	v_lshl_add_u64 v[0:1], s[6:7], 0, v[130:131]
	global_load_lds_dwordx4 v[0:1], off
	v_lshl_add_u64 v[0:1], s[6:7], 0, v[134:135]
	s_add_i32 m0, s39, 0x1e000
	s_mov_b64 s[6:7], 0xb0080
	global_load_lds_dwordx4 v[0:1], off
	v_bfe_u32 v0, v8, 4, 2
	v_and_b32_e32 v1, 15, v8
	v_lshlrev_b32_e32 v3, 4, v0
	v_lshl_or_b32 v186, s3, 6, v1
	v_lshl_or_b32 v1, v1, 6, v3
	v_lshlrev_b32_e32 v3, 2, v8
	v_and_b32_e32 v3, 32, v3
	v_lshlrev_b32_e32 v2, 3, v0
	v_bitop3_b32 v4, v1, s2, v3 bitop3:0xde
	v_bitop3_b32 v187, s5, v1, v3 bitop3:0xf6
	v_cmp_eq_u32_e64 s[2:3], 0, v0
	v_lshrrev_b32_e32 v1, 1, v13
	v_mul_lo_u32 v0, v15, s4
	s_mov_b32 s5, 0xb000
	v_mad_u64_u32 v[0:1], s[22:23], v1, s5, v[0:1]
	v_or_b32_e32 v0, v0, v14
	v_add_lshl_u32 v0, v0, v16, 1
	v_mov_b32_e32 v1, v131
	s_cmp_gt_i32 s18, 63
	v_lshl_add_u64 v[136:137], v[0:1], 0, s[6:7]
	v_lshrrev_b32_e32 v1, 1, v9
	v_mul_lo_u32 v0, v10, s4
	s_cselect_b64 s[18:19], -1, 0
	s_add_i32 s47, s44, -2
	v_mad_u64_u32 v[0:1], s[4:5], v1, s5, v[0:1]
	s_waitcnt vmcnt(8)
	s_barrier
	s_waitcnt vmcnt(6)
	s_cmpk_lt_u32 s20, 0x100
	v_or_b32_e32 v0, v0, v11
	s_cselect_b64 s[20:21], -1, 0
	v_add_lshl_u32 v0, v0, v12, 1
	v_mov_b32_e32 v1, v131
	s_add_i32 s50, 0, 0x10000
	s_add_i32 s51, 0, 0x14000
	v_lshl_or_b32 v188, s43, 5, v2
	s_ashr_i32 s48, s92, 31
	s_ashr_i32 s49, s34, 31
	v_lshl_add_u64 v[138:139], v[0:1], 0, s[6:7]
	v_mov_b64_e32 v[140:141], 0x200
	v_mov_b64_e32 v[142:143], 0x1ff
	v_add_u32_e32 v189, s50, v187
	v_add_u32_e32 v190, s51, v187
	v_add_u32_e32 v191, 0, v4
	s_mov_b32 s52, 0
	s_barrier
	s_branch .LBB0_894

; #define PG8_STAGE(bufoff, gbase, voff) do { _Pragma("unroll") for (int _i = 0; _i < 2; ++_i) \
;         __builtin_amdgcn_global_load_lds((const unsigned*)((const char*)(gbase) + (voff)[_i]), (LAS unsigned*)(lds + (bufoff) + ldsw + _i * 8192), 16, 0, 0); } while (0)
; #define PG8_WAIT_V(n) asm volatile("s_waitcnt vmcnt(" #n ")" ::: "memory")
; #define PG8_BAR __builtin_amdgcn_s_barrier()
; template <class Epi>
; __device__ __forceinline__ void gemm_phase(LAS unsigned char* lds, const int tid, const Gemm g, const StaticOrder& S, const Epi& E) {
;     ...
;     for (int i = 0; i < 2; ++i) { int R, C; stage_rc(tid * 16 + i * 8192, R, C); const int Rb = (R & ~31) + perm32(R & 31);
;         voffA[i] = (unsigned)(R * g.lda + C) * 2u; voffB[i] = (unsigned)(Rb * g.ldb + C) * 2u; }
;     const size_t kstep = (size_t)(BK * 2);
;     const size_t hstepA = (size_t)HALF * g.lda * 2, hstepB = (size_t)HALF * g.ldb * 2;
;     const size_t tstepA = 2 * hstepA, tstepB = 2 * hstepB;
;     const unsigned ldsw = (unsigned)wid * 1024u;
;     const int aoff = lds_byte(wr * 64 + fr, fq * 8), boff = lds_byte(wc * 32 + fr, fq * 8);
;     ...
;     PG8_STAGE(PG8_SB(0, 0), cB, voffB); PG8_STAGE(PG8_SB(0, 1), cB + hstepB, voffB); PG8_STAGE(PG8_SA(0, 0), cA, voffA); PG8_STAGE(PG8_SA(0, 1), cA + hstepA, voffA);
;     if (wr == 1) PG8_BAR;
;     PG8_WAIT_V(2); PG8_BAR;
;     PG8_STAGE(PG8_SB(1, 0), cB + kstep, voffB); PG8_STAGE(PG8_SA(1, 0), cA + kstep, voffA); PG8_STAGE(PG8_SB(1, 1), cB + hstepB + kstep, voffB);
;     PG8_WAIT_V(6); PG8_BAR;
.LBB0_938:
	s_add_u32 s6, s6, 0x19100000
	s_addc_u32 s7, s7, 0
	s_ashr_i32 s10, s4, 31
	s_lshr_b32 s10, s10, 26
	s_add_i32 s10, s4, s10
	s_ashr_i32 s44, s10, 6
	s_lshl_b32 s3, s3, 5
	s_mov_b64 s[10:11], 0x80
	s_and_b32 s3, s3, 0x60
	s_add_i32 m0, s40, 0x18000
	v_lshl_add_u64 v[6:7], v[6:7], 0, s[10:11]
	s_lshl_b32 s13, s12, 13
	s_lshl_b32 s15, s3, 7
	global_load_lds_dwordx4 v[6:7], off
	v_lshl_add_u64 v[4:5], v[4:5], 0, s[10:11]
	s_add_i32 m0, s40, 0x1a000
	s_add_i32 s45, s40, 0x8000
	s_add_i32 s46, s40, 0xa000
	global_load_lds_dwordx4 v[4:5], off
	v_lshl_add_u64 v[0:1], v[0:1], 0, s[10:11]
	s_mov_b32 m0, s45
	s_add_u32 s18, s26, 0x10080
	global_load_lds_dwordx4 v[0:1], off
	v_lshl_add_u64 v[0:1], v[2:3], 0, s[10:11]
	s_mov_b32 m0, s46
	s_addc_u32 s19, s27, 0
	global_load_lds_dwordx4 v[0:1], off
	s_add_i32 m0, s40, 0x1c000
	v_lshl_add_u64 v[0:1], s[18:19], 0, v[130:131]
	global_load_lds_dwordx4 v[0:1], off
	v_lshl_add_u64 v[0:1], s[18:19], 0, v[134:135]
	s_add_i32 m0, s40, 0x1e000
	s_cmp_gt_i32 s4, 63
	global_load_lds_dwordx4 v[0:1], off
	v_lshrrev_b32_e32 v0, 1, v8
	v_and_b32_e32 v0, 24, v0
	v_and_b32_e32 v1, 15, v8
	v_lshlrev_b32_e32 v2, 1, v0
	v_lshl_or_b32 v146, s12, 6, v1
	v_lshl_or_b32 v1, v1, 6, v2
	v_lshlrev_b32_e32 v2, 2, v8
	v_and_b32_e32 v2, 32, v2
	v_bitop3_b32 v3, v1, s13, v2 bitop3:0xde
	v_bitop3_b32 v147, s15, v1, v2 bitop3:0xf6
	v_lshlrev_b32_e32 v1, 12, v12
	v_and_b32_e32 v1, 0xffffe000, v1
	v_lshl_add_u32 v1, v13, 9, v1
	v_and_b32_e32 v2, 1, v12
	v_lshl_or_b32 v1, v2, 6, v1
	v_lshl_add_u32 v138, v14, 1, v1
	v_lshlrev_b32_e32 v1, 12, v9
	s_cselect_b64 s[12:13], -1, 0
	s_add_i32 s47, s44, -2
	v_and_b32_e32 v1, 0xffffe000, v1
	s_waitcnt vmcnt(8)
	s_barrier
	s_waitcnt vmcnt(6)
	s_cmpk_lt_u32 s14, 0x100
	v_lshl_add_u32 v1, v10, 9, v1
	v_and_b32_e32 v2, 1, v9
	s_cselect_b64 s[14:15], -1, 0
	v_lshl_or_b32 v1, v2, 6, v1
	s_add_i32 s49, 0, 0x10000
	s_add_i32 s50, 0, 0x14000
	s_sext_i32_i8 s17, s2
	s_ashr_i32 s48, s92, 31
	v_mov_b32_e32 v139, v137
	v_lshl_add_u32 v140, v11, 1, v1
	v_mov_b32_e32 v141, v137
	v_mov_b64_e32 v[142:143], 0x200
	v_mov_b64_e32 v[144:145], 0x1ff
	v_add_u32_e32 v148, s49, v147
	v_add_u32_e32 v149, s50, v147
	v_add_u32_e32 v150, 0, v3
	s_lshl_b32 s4, s3, 1
	v_lshlrev_b32_e32 v136, 1, v0
	s_mov_b32 s51, s5
	s_barrier
	s_branch .LBB0_941

; #define PG8_STAGE(bufoff, gbase, voff) do { _Pragma("unroll") for (int _i = 0; _i < 2; ++_i) \
;         __builtin_amdgcn_global_load_lds((const unsigned*)((const char*)(gbase) + (voff)[_i]), (LAS unsigned*)(lds + (bufoff) + ldsw + _i * 8192), 16, 0, 0); } while (0)
; #define PG8_WAIT_V(n) asm volatile("s_waitcnt vmcnt(" #n ")" ::: "memory")
; #define PG8_BAR __builtin_amdgcn_s_barrier()
; template <class Epi>
; __device__ __forceinline__ void gemm_phase(LAS unsigned char* lds, const int tid, const Gemm g, const StaticOrder& S, const Epi& E) {
;     ...
;     for (int i = 0; i < 2; ++i) { int R, C; stage_rc(tid * 16 + i * 8192, R, C); const int Rb = (R & ~31) + perm32(R & 31);
;         voffA[i] = (unsigned)(R * g.lda + C) * 2u; voffB[i] = (unsigned)(Rb * g.ldb + C) * 2u; }
;     const size_t kstep = (size_t)(BK * 2);
;     const size_t hstepA = (size_t)HALF * g.lda * 2, hstepB = (size_t)HALF * g.ldb * 2;
;     const size_t tstepA = 2 * hstepA, tstepB = 2 * hstepB;
;     const unsigned ldsw = (unsigned)wid * 1024u;
;     const int aoff = lds_byte(wr * 64 + fr, fq * 8), boff = lds_byte(wc * 32 + fr, fq * 8);
;     ...
;     PG8_STAGE(PG8_SB(0, 0), cB, voffB); PG8_STAGE(PG8_SB(0, 1), cB + hstepB, voffB); PG8_STAGE(PG8_SA(0, 0), cA, voffA); PG8_STAGE(PG8_SA(0, 1), cA + hstepA, voffA);
;     if (wr == 1) PG8_BAR;
;     PG8_WAIT_V(2); PG8_BAR;
;     PG8_STAGE(PG8_SB(1, 0), cB + kstep, voffB); PG8_STAGE(PG8_SA(1, 0), cA + kstep, voffA); PG8_STAGE(PG8_SB(1, 1), cB + hstepB + kstep, voffB);
;     PG8_WAIT_V(6); PG8_BAR;
.LBB0_1021:
	s_add_u32 s14, s6, 0x19100000
	s_addc_u32 s15, s7, 0
	s_add_u32 s16, s6, 0xa100000
	s_addc_u32 s17, s7, 0
	s_add_u32 s18, s6, 0x1f100000
	s_addc_u32 s19, s7, 0
	s_and_b32 s52, s2, 3
	s_ashr_i32 s2, s22, 31
	s_lshr_b32 s2, s2, 26
	s_mov_b64 s[20:21], 0x80
	s_add_i32 s2, s22, s2
	s_add_i32 m0, s48, 0x18000
	v_lshl_add_u64 v[8:9], v[8:9], 0, s[20:21]
	s_ashr_i32 s53, s2, 6
	s_lshl_b32 s2, s3, 13
	s_lshl_b32 s23, s52, 12
	global_load_lds_dwordx4 v[8:9], off
	v_lshl_add_u64 v[6:7], v[6:7], 0, s[20:21]
	s_add_i32 m0, s48, 0x1a000
	s_add_i32 s54, s48, 0x8000
	s_add_i32 s55, s48, 0xa000
	global_load_lds_dwordx4 v[6:7], off
	v_lshl_add_u64 v[2:3], v[2:3], 0, s[20:21]
	s_mov_b32 m0, s54
	s_add_u32 s4, s38, 0x40080
	global_load_lds_dwordx4 v[2:3], off
	v_lshl_add_u64 v[2:3], v[4:5], 0, s[20:21]
	s_mov_b32 m0, s55
	s_addc_u32 s5, s39, 0
	global_load_lds_dwordx4 v[2:3], off
	s_add_i32 m0, s48, 0x1c000
	v_lshl_add_u64 v[2:3], s[4:5], 0, v[182:183]
	global_load_lds_dwordx4 v[2:3], off
	v_lshl_add_u64 v[2:3], s[4:5], 0, v[186:187]
	s_add_i32 m0, s48, 0x1e000
	v_lshl_add_u64 v[0:1], v[0:1], 4, s[6:7]
	global_load_lds_dwordx4 v[2:3], off
	s_mov_b64 s[4:5], 0x1f300000
	v_lshl_add_u64 v[188:189], v[0:1], 0, s[4:5]
	v_lshlrev_b32_e32 v0, 14, v14
	v_and_b32_e32 v0, 0xffff8000, v0
	v_and_b32_e32 v3, 15, v10
	v_lshl_add_u32 v0, v15, 11, v0
	v_and_b32_e32 v1, 1, v14
	v_bfe_u32 v2, v10, 4, 2
	v_lshl_or_b32 v208, s3, 6, v3
	v_lshl_or_b32 v0, v1, 6, v0
	v_lshlrev_b32_e32 v5, 6, v208
	v_lshlrev_b32_e32 v6, 4, v2
	s_movk_i32 s3, 0x3c0
	v_lshlrev_b32_e32 v8, 2, v10
	v_lshl_add_u32 v190, v16, 1, v0
	v_lshlrev_b32_e32 v0, 14, v11
	v_and_or_b32 v7, v5, s3, v6
	v_and_b32_e32 v8, 32, v8
	v_lshl_or_b32 v3, v3, 6, v6
	s_cmp_gt_i32 s22, 63
	v_and_b32_e32 v0, 0xffff8000, v0
	v_bitop3_b32 v7, v7, s2, v8 bitop3:0xde
	v_bitop3_b32 v209, s23, v3, v8 bitop3:0xf6
	s_waitcnt vmcnt(8)
	s_barrier
	s_waitcnt vmcnt(6)
	s_cselect_b64 s[22:23], -1, 0
	s_add_i32 s2, 0, 0x20800
	s_add_i32 s56, s53, -2
	v_lshl_add_u32 v0, v12, 11, v0
	v_and_b32_e32 v1, 1, v11
	v_lshlrev_b32_e32 v4, 3, v2
	v_add_u32_e32 v3, s2, v5
	s_cmpk_lt_u32 s24, 0x100
	v_lshl_or_b32 v0, v1, 6, v0
	v_lshl_or_b32 v210, s52, 5, v4
	s_cselect_b64 s[24:25], -1, 0
	v_cmp_eq_u32_e64 s[2:3], 0, v2
	s_ashr_i32 s57, s92, 31
	s_ashr_i32 s58, s44, 31
	v_mov_b32_e32 v191, v183
	v_lshl_add_u32 v192, v13, 1, v0
	v_mov_b32_e32 v193, v183
	v_mov_b64_e32 v[194:195], 0x200
	v_mov_b64_e32 v[196:197], 0x1ff
	s_mov_b64 s[6:7], 0x2000
	s_add_i32 s59, 0, 0x10000
	s_add_i32 s60, 0, 0x14000
	v_add_u32_e32 v211, 0, v7
	v_mov_b32_e32 v212, 0x358637bd
	v_add_u32_e32 v213, v3, v6
	s_mov_b32 s61, 0
	s_barrier
	s_branch .LBB0_1024

; #define PG8_STAGE(bufoff, gbase, voff) do { _Pragma("unroll") for (int _i = 0; _i < 2; ++_i) \
;         __builtin_amdgcn_global_load_lds((const unsigned*)((const char*)(gbase) + (voff)[_i]), (LAS unsigned*)(lds + (bufoff) + ldsw + _i * 8192), 16, 0, 0); } while (0)
; #define PG8_WAIT_V(n) asm volatile("s_waitcnt vmcnt(" #n ")" ::: "memory")
; #define PG8_BAR __builtin_amdgcn_s_barrier()
; template <class Epi>
; __device__ __forceinline__ void gemm_phase(LAS unsigned char* lds, const int tid, const Gemm g, const StaticOrder& S, const Epi& E) {
;     ...
;     for (int i = 0; i < 2; ++i) { int R, C; stage_rc(tid * 16 + i * 8192, R, C); const int Rb = (R & ~31) + perm32(R & 31);
;         voffA[i] = (unsigned)(R * g.lda + C) * 2u; voffB[i] = (unsigned)(Rb * g.ldb + C) * 2u; }
;     const size_t kstep = (size_t)(BK * 2);
;     const size_t hstepA = (size_t)HALF * g.lda * 2, hstepB = (size_t)HALF * g.ldb * 2;
;     const size_t tstepA = 2 * hstepA, tstepB = 2 * hstepB;
;     const unsigned ldsw = (unsigned)wid * 1024u;
;     const int aoff = lds_byte(wr * 64 + fr, fq * 8), boff = lds_byte(wc * 32 + fr, fq * 8);
;     ...
;     PG8_STAGE(PG8_SB(0, 0), cB, voffB); PG8_STAGE(PG8_SB(0, 1), cB + hstepB, voffB); PG8_STAGE(PG8_SA(0, 0), cA, voffA); PG8_STAGE(PG8_SA(0, 1), cA + hstepA, voffA);
;     if (wr == 1) PG8_BAR;
;     PG8_WAIT_V(2); PG8_BAR;
;     PG8_STAGE(PG8_SB(1, 0), cB + kstep, voffB); PG8_STAGE(PG8_SA(1, 0), cA + kstep, voffA); PG8_STAGE(PG8_SB(1, 1), cB + hstepB + kstep, voffB);
;     PG8_WAIT_V(6); PG8_BAR;
.LBB0_1197:
	s_add_u32 s12, s6, 0xa100000
	s_addc_u32 s13, s7, 0
	s_add_u32 s14, s6, 0x1f300000
	s_addc_u32 s15, s7, 0
	s_and_b32 s43, s2, 3
	s_ashr_i32 s2, s18, 31
	s_lshr_b32 s2, s2, 26
	s_mov_b64 s[16:17], 0x80
	s_add_i32 s2, s18, s2
	s_add_i32 m0, s39, 0x18000
	v_lshl_add_u64 v[6:7], v[6:7], 0, s[16:17]
	s_ashr_i32 s44, s2, 6
	s_lshl_b32 s2, s3, 13
	s_lshl_b32 s5, s43, 12
	global_load_lds_dwordx4 v[6:7], off
	v_lshl_add_u64 v[4:5], v[4:5], 0, s[16:17]
	s_add_i32 m0, s39, 0x1a000
	s_add_i32 s45, s39, 0x8000
	s_add_i32 s46, s39, 0xa000
	global_load_lds_dwordx4 v[4:5], off
	v_lshl_add_u64 v[0:1], v[0:1], 0, s[16:17]
	s_mov_b32 m0, s45
	s_add_u32 s6, s26, 0xb0080
	global_load_lds_dwordx4 v[0:1], off
	v_lshl_add_u64 v[0:1], v[2:3], 0, s[16:17]
	s_mov_b32 m0, s46
	s_addc_u32 s7, s27, 0
	global_load_lds_dwordx4 v[0:1], off
	s_add_i32 m0, s39, 0x1c000
	v_lshl_add_u64 v[0:1], s[6:7], 0, v[130:131]
	global_load_lds_dwordx4 v[0:1], off
	v_lshl_add_u64 v[0:1], s[6:7], 0, v[134:135]
	s_add_i32 m0, s39, 0x1e000
	s_mov_b64 s[6:7], 0xb0080
	global_load_lds_dwordx4 v[0:1], off
	v_bfe_u32 v0, v8, 4, 2
	v_and_b32_e32 v1, 15, v8
	v_lshlrev_b32_e32 v3, 4, v0
	v_lshl_or_b32 v186, s3, 6, v1
	v_lshl_or_b32 v1, v1, 6, v3
	v_lshlrev_b32_e32 v3, 2, v8
	v_and_b32_e32 v3, 32, v3
	v_lshlrev_b32_e32 v2, 3, v0
	v_bitop3_b32 v4, v1, s2, v3 bitop3:0xde
	v_bitop3_b32 v187, s5, v1, v3 bitop3:0xf6
	v_cmp_eq_u32_e64 s[2:3], 0, v0
	v_lshrrev_b32_e32 v1, 1, v13
	v_mul_lo_u32 v0, v15, s4
	s_mov_b32 s5, 0xb000
	v_mad_u64_u32 v[0:1], s[22:23], v1, s5, v[0:1]
	v_or_b32_e32 v0, v0, v14
	v_add_lshl_u32 v0, v0, v16, 1
	v_mov_b32_e32 v1, v131
	s_cmp_gt_i32 s18, 63
	v_lshl_add_u64 v[136:137], v[0:1], 0, s[6:7]
	v_lshrrev_b32_e32 v1, 1, v9
	v_mul_lo_u32 v0, v10, s4
	s_cselect_b64 s[18:19], -1, 0
	s_add_i32 s47, s44, -2
	v_mad_u64_u32 v[0:1], s[4:5], v1, s5, v[0:1]
	s_waitcnt vmcnt(8)
	s_barrier
	s_waitcnt vmcnt(6)
	s_cmpk_lt_u32 s20, 0x100
	v_or_b32_e32 v0, v0, v11
	s_cselect_b64 s[20:21], -1, 0
	v_add_lshl_u32 v0, v0, v12, 1
	v_mov_b32_e32 v1, v131
	s_add_i32 s50, 0, 0x10000
	s_add_i32 s51, 0, 0x14000
	v_lshl_or_b32 v188, s43, 5, v2
	s_ashr_i32 s48, s92, 31
	s_ashr_i32 s49, s34, 31
	v_lshl_add_u64 v[138:139], v[0:1], 0, s[6:7]
	v_mov_b64_e32 v[140:141], 0x200
	v_mov_b64_e32 v[142:143], 0x1ff
	v_add_u32_e32 v189, s50, v187
	v_add_u32_e32 v190, s51, v187
	v_add_u32_e32 v191, 0, v4
	s_mov_b32 s52, 0
	s_barrier
	s_branch .LBB0_1200

; #define PG8_STAGE(bufoff, gbase, voff) do { _Pragma("unroll") for (int _i = 0; _i < 2; ++_i) \
;         __builtin_amdgcn_global_load_lds((const unsigned*)((const char*)(gbase) + (voff)[_i]), (LAS unsigned*)(lds + (bufoff) + ldsw + _i * 8192), 16, 0, 0); } while (0)
; #define PG8_WAIT_V(n) asm volatile("s_waitcnt vmcnt(" #n ")" ::: "memory")
; #define PG8_BAR __builtin_amdgcn_s_barrier()
; template <class Epi>
; __device__ __forceinline__ void gemm_phase(LAS unsigned char* lds, const int tid, const Gemm g, const StaticOrder& S, const Epi& E) {
;     ...
;     for (int i = 0; i < 2; ++i) { int R, C; stage_rc(tid * 16 + i * 8192, R, C); const int Rb = (R & ~31) + perm32(R & 31);
;         voffA[i] = (unsigned)(R * g.lda + C) * 2u; voffB[i] = (unsigned)(Rb * g.ldb + C) * 2u; }
;     const size_t kstep = (size_t)(BK * 2);
;     const size_t hstepA = (size_t)HALF * g.lda * 2, hstepB = (size_t)HALF * g.ldb * 2;
;     const size_t tstepA = 2 * hstepA, tstepB = 2 * hstepB;
;     const unsigned ldsw = (unsigned)wid * 1024u;
;     const int aoff = lds_byte(wr * 64 + fr, fq * 8), boff = lds_byte(wc * 32 + fr, fq * 8);
;     ...
;     PG8_STAGE(PG8_SB(0, 0), cB, voffB); PG8_STAGE(PG8_SB(0, 1), cB + hstepB, voffB); PG8_STAGE(PG8_SA(0, 0), cA, voffA); PG8_STAGE(PG8_SA(0, 1), cA + hstepA, voffA);
;     if (wr == 1) PG8_BAR;
;     PG8_WAIT_V(2); PG8_BAR;
;     PG8_STAGE(PG8_SB(1, 0), cB + kstep, voffB); PG8_STAGE(PG8_SA(1, 0), cA + kstep, voffA); PG8_STAGE(PG8_SB(1, 1), cB + hstepB + kstep, voffB);
;     PG8_WAIT_V(6); PG8_BAR;
.LBB0_1301:
	s_ashr_i32 s5, s12, 31
	s_lshr_b32 s5, s5, 26
	s_lshl_b32 s3, s3, 5
	s_mov_b64 s[10:11], 0x80
	s_add_i32 s5, s12, s5
	s_and_b32 s18, s3, 0x60
	s_add_i32 m0, s27, 0x18000
	v_lshl_add_u64 v[8:9], v[8:9], 0, s[10:11]
	s_ashr_i32 s46, s5, 6
	s_lshl_b32 s5, s2, 13
	s_lshl_b32 s3, s18, 7
	global_load_lds_dwordx4 v[8:9], off
	v_lshl_add_u64 v[6:7], v[6:7], 0, s[10:11]
	s_add_i32 m0, s27, 0x1a000
	s_add_i32 s47, s27, 0x8000
	s_add_i32 s48, s27, 0xa000
	global_load_lds_dwordx4 v[6:7], off
	v_lshl_add_u64 v[2:3], v[2:3], 0, s[10:11]
	s_mov_b32 m0, s47
	s_add_u32 s16, s28, 0x40080
	global_load_lds_dwordx4 v[2:3], off
	v_lshl_add_u64 v[2:3], v[4:5], 0, s[10:11]
	s_mov_b32 m0, s48
	s_addc_u32 s17, s29, 0
	global_load_lds_dwordx4 v[2:3], off
	s_add_i32 m0, s27, 0x1c000
	v_lshl_add_u64 v[2:3], s[16:17], 0, v[130:131]
	global_load_lds_dwordx4 v[2:3], off
	v_lshl_add_u64 v[2:3], s[16:17], 0, v[134:135]
	s_add_i32 m0, s27, 0x1e000
	v_and_b32_e32 v4, 15, v10
	global_load_lds_dwordx4 v[2:3], off
	v_bfe_u32 v3, v10, 4, 2
	v_lshl_or_b32 v156, s2, 6, v4
	v_lshlrev_b32_e32 v2, 3, v3
	v_lshlrev_b32_e32 v5, 6, v156
	v_lshlrev_b32_e32 v3, 4, v3
	s_movk_i32 s2, 0x3c0
	v_lshlrev_b32_e32 v7, 2, v10
	s_cmp_gt_i32 s12, 63
	v_and_or_b32 v6, v5, s2, v3
	v_and_b32_e32 v7, 32, v7
	v_lshl_or_b32 v4, v4, 6, v3
	s_cselect_b64 s[12:13], -1, 0
	s_add_i32 s2, 0, 0x20800
	v_bitop3_b32 v157, s3, v4, v7 bitop3:0xf6
	v_add_u32_e32 v4, s2, v5
	v_lshl_add_u64 v[0:1], v[0:1], 4, s[6:7]
	s_mov_b64 s[2:3], 0x1f300000
	v_lshl_add_u64 v[138:139], v[0:1], 0, s[2:3]
	v_lshlrev_b32_e32 v0, 14, v14
	v_and_b32_e32 v0, 0xffff8000, v0
	v_lshl_add_u32 v0, v15, 11, v0
	v_and_b32_e32 v1, 1, v14
	v_lshl_or_b32 v0, v1, 6, v0
	v_lshl_add_u32 v140, v16, 1, v0
	v_lshlrev_b32_e32 v0, 14, v11
	v_and_b32_e32 v0, 0xffff8000, v0
	s_waitcnt vmcnt(8)
	s_barrier
	s_waitcnt vmcnt(6)
	s_add_i32 s49, s46, -2
	v_lshl_add_u32 v0, v12, 11, v0
	v_and_b32_e32 v1, 1, v11
	v_bitop3_b32 v6, v6, s5, v7 bitop3:0xde
	s_cmpk_lt_u32 s14, 0x100
	v_lshl_or_b32 v0, v1, 6, v0
	s_cselect_b64 s[14:15], -1, 0
	s_ashr_i32 s50, s92, 31
	s_ashr_i32 s51, s36, 31
	v_mov_b32_e32 v141, v137
	v_lshl_add_u32 v142, v13, 1, v0
	v_mov_b32_e32 v143, v137
	v_mov_b64_e32 v[144:145], 0x400
	v_mov_b64_e32 v[146:147], 0x3ff
	s_mov_b64 s[16:17], 0x2000
	s_add_i32 s52, 0, 0x10000
	s_add_i32 s53, 0, 0x14000
	v_add_u32_e32 v158, 0, v6
	v_mov_b32_e32 v159, 0x358637bd
	s_mov_b32 s54, 0x6100000
	s_lshl_b32 s55, s18, 1
	v_lshlrev_b32_e32 v136, 1, v2
	v_add_u32_e32 v160, v4, v3
	s_barrier
	s_branch .LBB0_1304

; #define PG8_STAGE(bufoff, gbase, voff) do { _Pragma("unroll") for (int _i = 0; _i < 2; ++_i) \
;         __builtin_amdgcn_global_load_lds((const unsigned*)((const char*)(gbase) + (voff)[_i]), (LAS unsigned*)(lds + (bufoff) + ldsw + _i * 8192), 16, 0, 0); } while (0)
; #define PG8_WAIT_V(n) asm volatile("s_waitcnt vmcnt(" #n ")" ::: "memory")
; #define PG8_BAR __builtin_amdgcn_s_barrier()
; template <class Epi>
; __device__ __forceinline__ void gemm_phase(LAS unsigned char* lds, const int tid, const Gemm g, const StaticOrder& S, const Epi& E) {
;     ...
;     for (int i = 0; i < 2; ++i) { int R, C; stage_rc(tid * 16 + i * 8192, R, C); const int Rb = (R & ~31) + perm32(R & 31);
;         voffA[i] = (unsigned)(R * g.lda + C) * 2u; voffB[i] = (unsigned)(Rb * g.ldb + C) * 2u; }
;     const size_t kstep = (size_t)(BK * 2);
;     const size_t hstepA = (size_t)HALF * g.lda * 2, hstepB = (size_t)HALF * g.ldb * 2;
;     const size_t tstepA = 2 * hstepA, tstepB = 2 * hstepB;
;     const unsigned ldsw = (unsigned)wid * 1024u;
;     const int aoff = lds_byte(wr * 64 + fr, fq * 8), boff = lds_byte(wc * 32 + fr, fq * 8);
;     ...
;     PG8_STAGE(PG8_SB(0, 0), cB, voffB); PG8_STAGE(PG8_SB(0, 1), cB + hstepB, voffB); PG8_STAGE(PG8_SA(0, 0), cA, voffA); PG8_STAGE(PG8_SA(0, 1), cA + hstepA, voffA);
;     if (wr == 1) PG8_BAR;
;     PG8_WAIT_V(2); PG8_BAR;
;     PG8_STAGE(PG8_SB(1, 0), cB + kstep, voffB); PG8_STAGE(PG8_SA(1, 0), cA + kstep, voffA); PG8_STAGE(PG8_SB(1, 1), cB + hstepB + kstep, voffB);
;     PG8_WAIT_V(6); PG8_BAR;
.LBB0_1514:
	s_ashr_i32 s5, s12, 3
	s_add_u32 s12, s10, 0x1fa10000
	s_addc_u32 s13, s11, 0
	s_add_u32 s10, s10, 0xe100000
	s_addc_u32 s11, s11, 0
	s_add_u32 s14, s8, 0x4000000
	s_addc_u32 s15, s9, 0
	s_ashr_i32 s16, s22, 31
	s_lshr_b32 s16, s16, 26
	s_add_i32 s16, s22, s16
	s_ashr_i32 s52, s16, 6
	s_lshl_b32 s2, s2, 5
	s_mov_b64 s[16:17], 0x80
	s_and_b32 s2, s2, 0x60
	s_add_i32 m0, s47, 0x18000
	v_lshl_add_u64 v[6:7], v[6:7], 0, s[16:17]
	s_lshl_b32 s23, s3, 13
	s_lshl_b32 s25, s2, 7
	global_load_lds_dwordx4 v[6:7], off
	v_lshl_add_u64 v[4:5], v[4:5], 0, s[16:17]
	s_add_i32 m0, s47, 0x1a000
	s_add_i32 s53, s47, 0x8000
	s_add_i32 s54, s47, 0xa000
	global_load_lds_dwordx4 v[4:5], off
	v_lshl_add_u64 v[0:1], v[0:1], 0, s[16:17]
	s_mov_b32 m0, s53
	s_add_u32 s18, s36, 0x10080
	global_load_lds_dwordx4 v[0:1], off
	v_lshl_add_u64 v[0:1], v[2:3], 0, s[16:17]
	s_mov_b32 m0, s54
	s_addc_u32 s19, s37, 0
	global_load_lds_dwordx4 v[0:1], off
	s_add_i32 m0, s47, 0x1c000
	v_lshl_add_u64 v[0:1], s[18:19], 0, v[182:183]
	global_load_lds_dwordx4 v[0:1], off
	v_lshl_add_u64 v[0:1], s[18:19], 0, v[186:187]
	s_add_i32 m0, s47, 0x1e000
	s_cmp_gt_i32 s22, 63
	global_load_lds_dwordx4 v[0:1], off
	v_lshrrev_b32_e32 v1, 1, v8
	v_and_b32_e32 v1, 24, v1
	v_and_b32_e32 v0, 15, v8
	v_lshlrev_b32_e32 v2, 1, v1
	v_lshl_or_b32 v214, s3, 6, v0
	v_lshl_or_b32 v0, v0, 6, v2
	v_lshlrev_b32_e32 v2, 2, v8
	v_and_b32_e32 v2, 32, v2
	v_bitop3_b32 v3, v0, s23, v2 bitop3:0xde
	v_bitop3_b32 v215, s25, v0, v2 bitop3:0xf6
	v_lshlrev_b32_e32 v0, 14, v12
	v_and_b32_e32 v0, 0xffff8000, v0
	v_or_b32_e32 v216, s2, v1
	v_lshl_add_u32 v0, v13, 11, v0
	v_and_b32_e32 v1, 1, v12
	v_lshl_or_b32 v0, v1, 6, v0
	s_load_dwordx2 s[18:19], s[0:1], 0x88
	s_load_dwordx2 s[20:21], s[0:1], 0x98
	v_lshl_add_u32 v188, v14, 1, v0
	v_lshlrev_b32_e32 v0, 14, v9
	s_cselect_b64 s[22:23], -1, 0
	s_add_i32 s55, s52, -2
	v_and_b32_e32 v0, 0xffff8000, v0
	s_waitcnt vmcnt(8)
	s_barrier
	s_waitcnt vmcnt(6)
	s_cmpk_lt_u32 s24, 0x100
	v_lshl_add_u32 v0, v10, 11, v0
	v_and_b32_e32 v1, 1, v9
	s_cselect_b64 s[24:25], -1, 0
	v_lshl_or_b32 v0, v1, 6, v0
	s_add_i32 s57, 0, 0x10000
	s_add_i32 s58, 0, 0x14000
	s_ashr_i32 s56, s92, 31
	v_mov_b32_e32 v189, v183
	v_lshl_add_u32 v190, v11, 1, v0
	v_mov_b32_e32 v191, v183
	v_mov_b64_e32 v[192:193], 0x400
	v_mov_b64_e32 v[194:195], 0x3ff
	v_add_u32_e32 v217, s57, v215
	v_add_u32_e32 v218, s58, v215
	v_add_u32_e32 v219, 0, v3
	v_mov_b32_e32 v220, 0x3c088889
	s_mov_b32 s59, 0xbe99999a
	s_mov_b32 s60, 0xf800000
	v_mov_b32_e32 v221, 0x260
	s_barrier
	s_branch .LBB0_1517

; #define PG8_STAGE(bufoff, gbase, voff) do { _Pragma("unroll") for (int _i = 0; _i < 2; ++_i) \
;         __builtin_amdgcn_global_load_lds((const unsigned*)((const char*)(gbase) + (voff)[_i]), (LAS unsigned*)(lds + (bufoff) + ldsw + _i * 8192), 16, 0, 0); } while (0)
; #define PG8_WAIT_V(n) asm volatile("s_waitcnt vmcnt(" #n ")" ::: "memory")
; #define PG8_BAR __builtin_amdgcn_s_barrier()
; template <class Epi>
; __device__ __forceinline__ void gemm_phase(LAS unsigned char* lds, const int tid, const Gemm g, const StaticOrder& S, const Epi& E) {
;     ...
;     for (int i = 0; i < 2; ++i) { int R, C; stage_rc(tid * 16 + i * 8192, R, C); const int Rb = (R & ~31) + perm32(R & 31);
;         voffA[i] = (unsigned)(R * g.lda + C) * 2u; voffB[i] = (unsigned)(Rb * g.ldb + C) * 2u; }
;     const size_t kstep = (size_t)(BK * 2);
;     const size_t hstepA = (size_t)HALF * g.lda * 2, hstepB = (size_t)HALF * g.ldb * 2;
;     const size_t tstepA = 2 * hstepA, tstepB = 2 * hstepB;
;     const unsigned ldsw = (unsigned)wid * 1024u;
;     const int aoff = lds_byte(wr * 64 + fr, fq * 8), boff = lds_byte(wc * 32 + fr, fq * 8);
;     ...
;     PG8_STAGE(PG8_SB(0, 0), cB, voffB); PG8_STAGE(PG8_SB(0, 1), cB + hstepB, voffB); PG8_STAGE(PG8_SA(0, 0), cA, voffA); PG8_STAGE(PG8_SA(0, 1), cA + hstepA, voffA);
;     if (wr == 1) PG8_BAR;
;     PG8_WAIT_V(2); PG8_BAR;
;     PG8_STAGE(PG8_SB(1, 0), cB + kstep, voffB); PG8_STAGE(PG8_SA(1, 0), cA + kstep, voffA); PG8_STAGE(PG8_SB(1, 1), cB + hstepB + kstep, voffB);
;     PG8_WAIT_V(6); PG8_BAR;
.LBB0_1723:
	s_add_u32 s14, s10, 0xa100000
	s_addc_u32 s15, s11, 0
	s_add_u32 s16, s10, 0x6100000
	s_addc_u32 s17, s11, 0
	s_add_u32 s10, s10, 0x1f100000
	s_addc_u32 s11, s11, 0
	s_and_b32 s49, s2, 3
	s_ashr_i32 s2, s20, 31
	s_lshr_b32 s2, s2, 26
	s_mov_b64 s[18:19], 0x80
	s_add_i32 s2, s20, s2
	s_add_i32 m0, s45, 0x18000
	v_lshl_add_u64 v[6:7], v[6:7], 0, s[18:19]
	s_ashr_i32 s50, s2, 6
	s_lshl_b32 s2, s3, 13
	s_lshl_b32 s21, s49, 12
	global_load_lds_dwordx4 v[6:7], off
	v_lshl_add_u64 v[4:5], v[4:5], 0, s[18:19]
	s_add_i32 m0, s45, 0x1a000
	s_add_i32 s51, s45, 0x8000
	s_add_i32 s52, s45, 0xa000
	global_load_lds_dwordx4 v[4:5], off
	v_lshl_add_u64 v[0:1], v[0:1], 0, s[18:19]
	s_mov_b32 m0, s51
	s_add_u32 s4, s36, 0x40080
	global_load_lds_dwordx4 v[0:1], off
	v_lshl_add_u64 v[0:1], v[2:3], 0, s[18:19]
	s_mov_b32 m0, s52
	s_addc_u32 s5, s37, 0
	global_load_lds_dwordx4 v[0:1], off
	s_add_i32 m0, s45, 0x1c000
	v_lshl_add_u64 v[0:1], s[4:5], 0, v[154:155]
	global_load_lds_dwordx4 v[0:1], off
	v_lshl_add_u64 v[0:1], s[4:5], 0, v[158:159]
	s_add_i32 m0, s45, 0x1e000
	s_cmp_gt_i32 s20, 63
	global_load_lds_dwordx4 v[0:1], off
	v_bfe_u32 v0, v8, 4, 2
	v_and_b32_e32 v1, 15, v8
	v_lshlrev_b32_e32 v3, 4, v0
	v_lshl_or_b32 v186, s3, 6, v1
	v_lshl_or_b32 v1, v1, 6, v3
	v_lshlrev_b32_e32 v3, 2, v8
	v_and_b32_e32 v3, 32, v3
	v_lshlrev_b32_e32 v2, 3, v0
	v_bitop3_b32 v4, v1, s2, v3 bitop3:0xde
	v_cmp_eq_u32_e64 s[2:3], 0, v0
	v_lshlrev_b32_e32 v0, 14, v12
	v_and_b32_e32 v0, 0xffff8000, v0
	v_bitop3_b32 v187, s21, v1, v3 bitop3:0xf6
	v_lshl_add_u32 v0, v13, 11, v0
	v_and_b32_e32 v1, 1, v12
	v_lshl_or_b32 v0, v1, 6, v0
	v_lshl_add_u32 v160, v14, 1, v0
	v_lshlrev_b32_e32 v0, 14, v9
	s_cselect_b64 s[20:21], -1, 0
	s_add_i32 s53, s50, -2
	v_and_b32_e32 v0, 0xffff8000, v0
	s_waitcnt vmcnt(8)
	s_barrier
	s_waitcnt vmcnt(6)
	s_cmpk_lt_u32 s22, 0x100
	v_lshl_add_u32 v0, v10, 11, v0
	v_and_b32_e32 v1, 1, v9
	s_cselect_b64 s[22:23], -1, 0
	v_lshl_or_b32 v0, v1, 6, v0
	s_add_i32 s56, 0, 0x10000
	s_add_i32 s57, 0, 0x14000
	v_lshl_or_b32 v188, s49, 5, v2
	s_ashr_i32 s54, s92, 31
	s_ashr_i32 s55, s33, 31
	v_mov_b32_e32 v161, v155
	v_lshl_add_u32 v162, v11, 1, v0
	v_mov_b32_e32 v163, v155
	v_mov_b64_e32 v[164:165], 0x200
	v_mov_b64_e32 v[166:167], 0x1ff
	v_add_u32_e32 v189, s56, v187
	v_add_u32_e32 v190, s57, v187
	v_add_u32_e32 v191, 0, v4
	s_mov_b32 s58, 0
	s_barrier
	s_branch .LBB0_1726

; #define PG8_STAGE(bufoff, gbase, voff) do { _Pragma("unroll") for (int _i = 0; _i < 2; ++_i) \
;         __builtin_amdgcn_global_load_lds((const unsigned*)((const char*)(gbase) + (voff)[_i]), (LAS unsigned*)(lds + (bufoff) + ldsw + _i * 8192), 16, 0, 0); } while (0)
; #define PG8_WAIT_V(n) asm volatile("s_waitcnt vmcnt(" #n ")" ::: "memory")
; #define PG8_BAR __builtin_amdgcn_s_barrier()
; template <class Epi>
; __device__ __forceinline__ void gemm_phase(LAS unsigned char* lds, const int tid, const Gemm g, const StaticOrder& S, const Epi& E) {
;     ...
;     for (int i = 0; i < 2; ++i) { int R, C; stage_rc(tid * 16 + i * 8192, R, C); const int Rb = (R & ~31) + perm32(R & 31);
;         voffA[i] = (unsigned)(R * g.lda + C) * 2u; voffB[i] = (unsigned)(Rb * g.ldb + C) * 2u; }
;     const size_t kstep = (size_t)(BK * 2);
;     const size_t hstepA = (size_t)HALF * g.lda * 2, hstepB = (size_t)HALF * g.ldb * 2;
;     const size_t tstepA = 2 * hstepA, tstepB = 2 * hstepB;
;     const unsigned ldsw = (unsigned)wid * 1024u;
;     const int aoff = lds_byte(wr * 64 + fr, fq * 8), boff = lds_byte(wc * 32 + fr, fq * 8);
;     ...
;     PG8_STAGE(PG8_SB(0, 0), cB, voffB); PG8_STAGE(PG8_SB(0, 1), cB + hstepB, voffB); PG8_STAGE(PG8_SA(0, 0), cA, voffA); PG8_STAGE(PG8_SA(0, 1), cA + hstepA, voffA);
;     if (wr == 1) PG8_BAR;
;     PG8_WAIT_V(2); PG8_BAR;
;     PG8_STAGE(PG8_SB(1, 0), cB + kstep, voffB); PG8_STAGE(PG8_SA(1, 0), cA + kstep, voffA); PG8_STAGE(PG8_SB(1, 1), cB + hstepB + kstep, voffB);
;     PG8_WAIT_V(6); PG8_BAR;
.LBB0_2025:
	s_add_u32 s10, s6, 0x19100000
	s_addc_u32 s11, s7, 0
	s_ashr_i32 s13, s14, 31
	s_lshr_b32 s13, s13, 26
	s_add_i32 s13, s14, s13
	s_lshl_b32 s12, s12, 5
	s_ashr_i32 s45, s13, 6
	s_and_b32 s20, s12, 0x60
	s_mov_b64 s[12:13], 0x80
	s_add_i32 m0, s40, 0x18000
	v_lshl_add_u64 v[8:9], v[8:9], 0, s[12:13]
	s_lshl_b32 s15, s1, 13
	s_lshl_b32 s17, s20, 7
	global_load_lds_dwordx4 v[8:9], off
	v_lshl_add_u64 v[6:7], v[6:7], 0, s[12:13]
	s_add_i32 m0, s40, 0x1a000
	s_add_i32 s46, s40, 0x8000
	s_add_i32 s47, s40, 0xa000
	global_load_lds_dwordx4 v[6:7], off
	v_lshl_add_u64 v[2:3], v[2:3], 0, s[12:13]
	s_mov_b32 m0, s46
	s_add_u32 s18, s28, 0x40080
	global_load_lds_dwordx4 v[2:3], off
	v_lshl_add_u64 v[2:3], v[4:5], 0, s[12:13]
	s_mov_b32 m0, s47
	s_addc_u32 s19, s29, 0
	global_load_lds_dwordx4 v[2:3], off
	s_add_i32 m0, s40, 0x1c000
	v_lshl_add_u64 v[2:3], s[18:19], 0, v[186:187]
	global_load_lds_dwordx4 v[2:3], off
	v_lshl_add_u64 v[2:3], s[18:19], 0, v[190:191]
	s_add_i32 m0, s40, 0x1e000
	s_sext_i32_i8 s33, s0
	global_load_lds_dwordx4 v[2:3], off
	v_and_b32_e32 v3, 15, v10
	v_bfe_u32 v2, v10, 4, 2
	v_lshl_or_b32 v212, s1, 6, v3
	v_lshlrev_b32_e32 v4, 6, v212
	v_lshlrev_b32_e32 v5, 4, v2
	s_movk_i32 s0, 0x3c0
	v_lshlrev_b32_e32 v7, 2, v10
	v_and_or_b32 v6, v4, s0, v5
	v_and_b32_e32 v7, 32, v7
	s_cmp_gt_i32 s14, 63
	v_bitop3_b32 v6, v6, s15, v7 bitop3:0xde
	v_lshl_or_b32 v3, v3, 6, v5
	s_cselect_b64 s[14:15], -1, 0
	s_add_i32 s0, 0, 0x20800
	v_bitop3_b32 v213, s17, v3, v7 bitop3:0xf6
	v_add_u32_e32 v3, s0, v4
	v_lshl_add_u64 v[0:1], v[0:1], 4, s[6:7]
	s_mov_b64 s[0:1], 0x1f300000
	v_lshl_add_u64 v[192:193], v[0:1], 0, s[0:1]
	v_lshlrev_b32_e32 v0, 14, v14
	v_and_b32_e32 v0, 0xffff8000, v0
	v_lshl_add_u32 v0, v15, 11, v0
	v_and_b32_e32 v1, 1, v14
	v_lshl_or_b32 v0, v1, 6, v0
	v_lshl_add_u32 v194, v16, 1, v0
	v_lshlrev_b32_e32 v0, 14, v11
	v_and_b32_e32 v0, 0xffff8000, v0
	s_waitcnt vmcnt(8)
	s_barrier
	s_waitcnt vmcnt(6)
	s_add_i32 s48, s45, -2
	v_lshl_add_u32 v0, v12, 11, v0
	v_and_b32_e32 v1, 1, v11
	s_cmpk_lt_u32 s16, 0x100
	v_lshl_or_b32 v0, v1, 6, v0
	s_cselect_b64 s[16:17], -1, 0
	s_ashr_i32 s49, s92, 31
	v_lshl_or_b32 v214, v2, 3, s20
	v_mov_b32_e32 v195, v187
	v_lshl_add_u32 v196, v13, 1, v0
	v_mov_b32_e32 v197, v187
	v_mov_b64_e32 v[198:199], 0x200
	v_mov_b64_e32 v[200:201], 0x1ff
	s_mov_b64 s[6:7], 0x2000
	s_add_i32 s50, 0, 0x10000
	s_add_i32 s51, 0, 0x14000
	v_add_u32_e32 v215, 0, v6
	v_add_u32_e32 v216, v3, v5
	v_mov_b32_e32 v217, 0x358637bd
	s_barrier
	s_branch .LBB0_2028
